# v22 plus state units remapped so the units of one (batch, head) run on the same XCD and share K/V tiles in L2 (phase was HBM-bound: 344 MB)
# speedup vs baseline: 1.0145x; 1.0085x over previous
; #define LAS __attribute__((address_space(3)))
; __device__ __forceinline__ void state_unit(LAS unsigned char* lds, const Args& a, int b, int hh, int dir, int eh, int wid, int lane) {
;     unsigned char* ws = a.ws;
;     asm volatile("" : "+v"(lane));
;     const int r = lane & 31, h = lane >> 5, tq = (lane & 15) >> 2, tp = lane & 3, g16 = (lane >> 4) & 1;
;     float lg2 = -log1pf(expf(-(dir ? a.dec_b[hh] : a.dec_f[hh]))) * 1.4426950408889634f;
;     lg2 = __uint_as_float(__builtin_amdgcn_readfirstlane(__float_as_uint(lg2)));
;     const float m = exp2f(dir ? lg2 : -lg2);
;     const float gch = exp2f((float)RCH * lg2);
;     const bf16_t* Kc = (const bf16_t*)(ws + WS_KC) + (size_t)(b * LCTX) * DM + hh * 256; const bf16_t* Vc = (const bf16_t*)(ws + WS_VC) + (size_t)(b * LCTX) * DM + hh * 256;
;     const bf16_t* Kl = (const bf16_t*)(ws + WS_K) + (size_t)(b * SEQ) * DM + hh * 256; const bf16_t* Vl = (const bf16_t*)(ws + WS_V) + (size_t)(b * SEQ) * DM + hh * 256;
;     bf16_t* ST = (bf16_t*)a.out + (size_t)MTOK * DM + (size_t)((b * 8 + hh) * 2 * NRCH) * 65536;
; __global__ void __launch_bounds__(512, 2) fwd_megakernel(Args a) {
;     ...
;     for (int idx = bx; idx < 256; idx += G) { state_unit(lds, a, idx >> 5, (idx >> 2) & 7, (idx >> 1) & 1, idx & 1, wid, lane); __syncthreads(); }
.LBB0_575:
	s_or_b64 exec, exec, s[0:1]
	s_andn2_b64 vcc, exec, s[48:49]
	s_waitcnt lgkmcnt(0)
	s_barrier
	s_cbranch_vccnz .LBB0_595
	s_lshl_b32 s0, s92, 2
	s_or_b32 s1, s0, 1
	s_lshl_b32 s7, s1, 1
	s_lshl_b32 s8, s1, 10
	s_or_b32 s1, s0, 2
	s_or_b32 s0, s0, 3
	s_lshl_b32 s11, s0, 1
	s_lshl_b32 s14, s0, 10
	s_lshl_b32 s0, s92, 1
	s_or_b32 s0, s0, 1
	s_lshl_b32 s22, s0, 2
	s_lshl_b32 s23, s0, 10
	s_and_b32 s0, s97, 0xffffff00
	s_add_i32 s34, s0, 0
	s_lshl_b32 s3, s92, 3
	s_lshl_b32 s6, s92, 12
	s_lshl_b32 s9, s1, 1
	s_lshl_b32 s10, s1, 10
	s_lshl_b32 s15, s92, 11
	s_lshl_b32 s33, s92, 5
	s_add_i32 s35, s34, 0x6800
	s_add_i32 s44, s34, 0x6000
	s_add_i32 s45, s34, 0x4800
	s_add_i32 s52, s34, 0x4000
	s_add_i32 s53, s34, 0x2800
	s_add_i32 s54, s34, 0x2000
	s_add_i32 s55, s34, 0x800
	s_add_u32 s56, s28, 0x1a380000
	s_mov_b32 s41, 0
	s_addc_u32 s57, s29, 0
	v_mov_b32_e32 v69, 0
	v_mov_b32_e32 v71, 0x7f800000
	v_mov_b32_e32 v128, 0x3ecc95a3
	v_mov_b32_e32 v129, 0xbfb8aa3b
	s_mov_b32 s58, 0xc2fc0000
	v_mov_b32_e32 v130, 0x42800000
	v_mov_b32_e32 v131, s6
	v_mov_b32_e32 v132, s8
	v_mov_b32_e32 v133, s10
	v_mov_b32_e32 v134, s14
	v_mov_b32_e32 v135, s15
	s_add_i32 s59, 0, 0x8000
	v_mov_b32_e32 v136, s23
	s_add_i32 s60, 0, 0xc000
	s_add_i32 s61, 0, 0x14000
	s_add_i32 s62, 0, 0xb400
	s_add_i32 s63, 0, 0xb000
	s_add_i32 s64, 0, 0xa400
	s_add_i32 s65, 0, 0xa000
	s_add_i32 s66, 0, 0x9400
	s_add_i32 s67, 0, 0x9000
	s_add_i32 s68, 0, 0x8400
	s_and_b32 s69, s2, 7
	s_lshl_b32 s69, s69, 2
	s_bfe_u32 s98, s2, 0x30003
	s_lshl_b32 s98, s98, 5
	s_or_b32 s69, s69, s98
	s_lshr_b32 s98, s2, 6
	s_or_b32 s69, s69, s98
	s_cmpk_eq_i32 s30, 0x100
	s_cselect_b32 s69, s69, s2
	s_branch .LBB0_578
